# FoX key loop: eight stop-vote words read with two ds_read_b128 instead of eight serial ds_read_b32 (six LDS round trips per step removed)
# baseline (speedup 1.0000x reference)
; #define LAS __attribute__((address_space(3)))
; template <int MODE> DI void attn_unit(int b, int qb, const bf16* Qb, int qpitch, const bf16* Kb, int kpitch, const bf16* VT, bf16* O, float* ssq, ...
;     ...
;         if (REV) {
;             int vote = 0;
;             if (seen && kt > 0) { const float fb0 = ((const LAS float*)(lds + FOFF + buf * 256))[0]; const float kb = MS[32 + ((kt - 1) >> 1)]; vote = __all((qn * kb + fb0 - m) < -40.0f) ? 1 : 0; }
;             volatile LAS int* vt = (volatile LAS int*)(MS + 64) + (it & 1) * 8;
;             if (lane == 0) vt[wave] = vote;
;             __syncthreads();
;             const int stop = vt[0] & vt[1] & vt[2] & vt[3] & vt[4] & vt[5] & vt[6] & vt[7];
;             if (stop) break;
.LBB0_500:
	s_or_b64 exec, exec, s[22:23]
	v_mov_b32_e32 v32, s26
	s_waitcnt lgkmcnt(0)
	s_barrier
	ds_read_b128 v[34:37], v32 offset:36608
	ds_read_b128 v[38:41], v32 offset:36624
	s_movk_i32 s26, 0xff80
	s_mov_b32 s27, -1
	v_lshl_add_u64 v[176:177], v[176:177], 0, s[26:27]
	s_movk_i32 s26, 0xfc00
	s_mov_b32 s27, -1
	v_lshl_add_u64 v[178:179], v[178:179], 0, s[26:27]
	s_mov_b32 s26, 0xfffc0000
	s_mov_b32 s27, -1
	s_xor_b32 s72, s72, 1
	s_add_i32 s61, s61, -1
	s_sub_i32 s59, s59, 64
	v_lshl_add_u64 v[180:181], v[180:181], 0, s[26:27]
	s_add_i32 s75, s75, 1
	s_add_i32 s74, s74, 8
	s_waitcnt lgkmcnt(0)
	v_and_b32_e32 v33, v34, v35
	v_and_b32_e32 v36, v36, v37
	v_and_b32_e32 v38, v38, v39
	v_and_b32_e32 v40, v40, v41
	v_and_b32_e32 v33, v33, v36
	v_and_b32_e32 v38, v38, v40
	v_and_b32_e32 v32, v33, v38
	v_cmp_ne_u32_e64 s[22:23], 0, v32
	s_and_b64 vcc, exec, s[22:23]
	s_cbranch_vccnz .LBB0_521
